# prompt attention: all four K/V row-group loads of a unit issued together before the unit barrier, counted vmcnt before each LDS write
# speedup vs baseline: 1.0126x; 1.0022x over previous
.LBB0_812:
	s_or_b64 exec, exec, s[52:53]
	s_ashr_i32 s49, s48, 31
	s_lshl_b64 s[48:49], s[48:49], 2
	s_add_u32 s48, s3, s48
	s_addc_u32 s49, s82, s49
	s_waitcnt lgkmcnt(0)
	s_barrier
	global_load_dword v149, v195, s[48:49]
	ds_read_b128 v[2:5], v142
	ds_read_b128 v[6:9], v142 offset:32
	s_waitcnt lgkmcnt(1)
	v_mfma_f32_32x32x16_bf16 v[66:81], v[2:5], v[34:37], 0
	ds_read_b128 v[2:5], v142 offset:64
	v_lshl_add_u64 v[126:127], s[50:51], 1, v[118:119]
	s_and_b64 s[48:49], vcc, s[12:13]
	s_and_b64 s[50:51], vcc, s[14:15]
	s_and_b64 s[52:53], vcc, s[16:17]
	s_and_b64 s[54:55], vcc, s[18:19]
	s_and_b64 s[56:57], vcc, s[20:21]
	s_waitcnt lgkmcnt(1)
	v_mfma_f32_32x32x16_bf16 v[66:81], v[6:9], v[106:109], v[66:81]
	s_and_b64 s[58:59], vcc, s[22:23]
	s_and_b64 s[60:61], vcc, s[24:25]
	s_and_b64 s[62:63], vcc, s[26:27]
	s_and_b64 s[64:65], vcc, s[28:29]
	s_and_b64 s[66:67], vcc, s[30:31]
	s_and_b64 s[68:69], vcc, s[34:35]
	s_and_b64 s[70:71], vcc, s[36:37]
	s_waitcnt lgkmcnt(0)
	v_mfma_f32_32x32x16_bf16 v[66:81], v[2:5], v[102:105], v[66:81]
	ds_read_b128 v[2:5], v142 offset:96
	s_and_b64 s[72:73], vcc, s[38:39]
	s_and_b64 s[74:75], vcc, s[42:43]
	s_and_b64 s[76:77], vcc, s[44:45]
	s_and_b64 s[78:79], vcc, s[0:1]
	s_or_b32 s80, s80, s96
	s_cmp_eq_u32 s80, 0
	s_waitcnt lgkmcnt(0)
	v_mfma_f32_32x32x16_bf16 v[66:81], v[2:5], v[98:101], v[66:81]
	ds_read_b128 v[2:5], v143
	ds_read_b128 v[6:9], v143 offset:32
	s_cselect_b64 s[80:81], -1, 0
	s_mov_b32 s94, 0x3fb8aa3b
	v_or_b32_e32 v152, s97, v150
	s_add_i32 s2, s2, s86
	s_cmpk_lt_i32 s2, 0x200
	s_nop 4
	v_cndmask_b32_e64 v67, v245, v67, s[50:51]
	s_waitcnt lgkmcnt(1)
	v_mfma_f32_32x32x16_bf16 v[50:65], v[2:5], v[34:37], 0
	ds_read_b128 v[2:5], v143 offset:64
	v_cndmask_b32_e64 v68, v245, v68, s[52:53]
	v_cndmask_b32_e64 v69, v245, v69, s[54:55]
	v_cndmask_b32_e64 v70, v245, v70, s[56:57]
	v_cndmask_b32_e64 v71, v245, v71, s[58:59]
	v_cndmask_b32_e64 v72, v245, v72, s[60:61]
	v_cndmask_b32_e64 v75, v245, v75, s[66:67]
	s_waitcnt lgkmcnt(1)
	v_mfma_f32_32x32x16_bf16 v[50:65], v[6:9], v[106:109], v[50:65]
	v_cndmask_b32_e64 v78, v245, v78, s[72:73]
	v_cndmask_b32_e64 v79, v245, v79, s[74:75]
	v_cndmask_b32_e64 v80, v245, v80, s[76:77]
	v_cndmask_b32_e64 v81, v245, v81, s[78:79]
	s_waitcnt vmcnt(0)
	v_mul_f32_e32 v151, 0x3fb8aa3b, v149
	s_waitcnt lgkmcnt(0)
	v_mfma_f32_32x32x16_bf16 v[50:65], v[2:5], v[102:105], v[50:65]
	ds_read_b128 v[2:5], v143 offset:96
	s_waitcnt lgkmcnt(0)
	v_mfma_f32_32x32x16_bf16 v[50:65], v[2:5], v[98:101], v[50:65]
	ds_read_b128 v[2:5], v144
	ds_read_b128 v[6:9], v144 offset:32
	s_waitcnt lgkmcnt(1)
	v_mfma_f32_32x32x16_bf16 v[18:33], v[2:5], v[34:37], 0
	ds_read_b128 v[2:5], v144 offset:64
	s_nop 6
	v_cndmask_b32_e32 v50, v245, v50, vcc
	v_cndmask_b32_e32 v54, v245, v54, vcc
	v_cndmask_b32_e32 v59, v245, v59, vcc
	v_cndmask_b32_e32 v60, v245, v60, vcc
	v_cndmask_b32_e32 v153, v245, v61, vcc
	v_cndmask_b32_e32 v63, v245, v63, vcc
	s_waitcnt lgkmcnt(1)
	v_mfma_f32_32x32x16_bf16 v[18:33], v[6:9], v[106:109], v[18:33]
	v_cndmask_b32_e32 v65, v245, v65, vcc
	s_waitcnt lgkmcnt(0)
	v_mfma_f32_32x32x16_bf16 v[18:33], v[2:5], v[102:105], v[18:33]
	ds_read_b128 v[2:5], v144 offset:96
	s_waitcnt lgkmcnt(0)
	v_mfma_f32_32x32x16_bf16 v[18:33], v[2:5], v[98:101], v[18:33]
	ds_read_b128 v[2:5], v145
	ds_read_b128 v[38:41], v145 offset:32
	s_waitcnt lgkmcnt(1)
	v_mfma_f32_32x32x16_bf16 v[2:17], v[2:5], v[34:37], 0
	s_nop 7
	v_cndmask_b32_e64 v158, v20, v245, s[80:81]
	v_cndmask_b32_e64 v159, v21, v245, s[80:81]
	v_cndmask_b32_e64 v160, v22, v245, s[80:81]
	v_cndmask_b32_e64 v161, v23, v245, s[80:81]
	v_cndmask_b32_e64 v162, v24, v245, s[80:81]
	v_cndmask_b32_e64 v163, v25, v245, s[80:81]
	v_cndmask_b32_e64 v164, v26, v245, s[80:81]
	s_waitcnt lgkmcnt(0)
	v_mfma_f32_32x32x16_bf16 v[2:17], v[38:41], v[106:109], v[2:17]
	ds_read_b128 v[38:41], v145 offset:64
	v_cndmask_b32_e64 v165, v27, v245, s[80:81]
	v_cndmask_b32_e64 v166, v28, v245, s[80:81]
	v_cndmask_b32_e64 v167, v29, v245, s[80:81]
	v_cndmask_b32_e64 v168, v30, v245, s[80:81]
	s_waitcnt lgkmcnt(0)
	v_mfma_f32_32x32x16_bf16 v[2:17], v[38:41], v[102:105], v[2:17]
	ds_read_b128 v[38:41], v145 offset:96
	s_waitcnt lgkmcnt(0)
	v_mfma_f32_32x32x16_bf16 v[2:17], v[38:41], v[98:101], v[2:17]
	ds_read_b128 v[38:41], v146
	ds_read_b128 v[154:157], v146 offset:32
	s_waitcnt lgkmcnt(1)
	v_mfma_f32_32x32x16_bf16 v[34:49], v[38:41], v[34:37], 0
	s_nop 7
	v_cndmask_b32_e64 v61, v5, v245, s[80:81]
	v_cndmask_b32_e64 v30, v14, v245, s[80:81]
	v_cndmask_b32_e64 v29, v15, v245, s[80:81]
	v_cndmask_b32_e64 v28, v16, v245, s[80:81]
	v_cndmask_b32_e64 v27, v17, v245, s[80:81]
	s_waitcnt lgkmcnt(0)
	v_mfma_f32_32x32x16_bf16 v[34:49], v[154:157], v[106:109], v[34:49]
	ds_read_b128 v[106:109], v146 offset:64
	v_cndmask_b32_e32 v154, v245, v62, vcc
	v_cndmask_b32_e32 v155, v245, v64, vcc
	v_cndmask_b32_e64 v156, v18, v245, s[80:81]
	v_cndmask_b32_e64 v157, v19, v245, s[80:81]
	v_cndmask_b32_e64 v64, v4, v245, s[80:81]
	s_waitcnt lgkmcnt(0)
	v_mfma_f32_32x32x16_bf16 v[34:49], v[106:109], v[102:105], v[34:49]
	ds_read_b128 v[102:105], v146 offset:96
	v_cndmask_b32_e32 v106, v245, v55, vcc
	v_cndmask_b32_e32 v107, v245, v56, vcc
	v_cndmask_b32_e32 v108, v245, v57, vcc
	v_cndmask_b32_e32 v109, v245, v58, vcc
	v_cndmask_b32_e64 v58, v6, v245, s[80:81]
	v_cndmask_b32_e64 v57, v7, v245, s[80:81]
	s_waitcnt lgkmcnt(0)
	v_mfma_f32_32x32x16_bf16 v[34:49], v[102:105], v[98:101], v[34:49]
	v_cndmask_b32_e64 v98, v245, v66, s[48:49]
	v_max3_f32 v66, v151, v98, v67
	v_max3_f32 v66, v66, v68, v69
	v_max3_f32 v66, v66, v70, v71
	v_cndmask_b32_e64 v99, v245, v73, s[62:63]
	v_max3_f32 v66, v66, v72, v99
	v_cndmask_b32_e64 v100, v245, v74, s[64:65]
	v_max3_f32 v66, v66, v100, v75
	v_cndmask_b32_e64 v101, v245, v76, s[68:69]
	v_cndmask_b32_e64 v102, v245, v77, s[70:71]
	v_max3_f32 v66, v66, v101, v102
	v_max3_f32 v66, v66, v78, v79
	v_max3_f32 v66, v66, v80, v81
	v_cndmask_b32_e32 v103, v245, v51, vcc
	v_max3_f32 v51, v66, v50, v103
	v_cndmask_b32_e32 v104, v245, v52, vcc
	v_cndmask_b32_e32 v105, v245, v53, vcc
	v_max3_f32 v51, v51, v104, v105
	v_max3_f32 v51, v51, v54, v106
	v_max3_f32 v51, v51, v107, v108
	v_max3_f32 v51, v51, v109, v59
	v_max3_f32 v51, v51, v60, v153
	v_max3_f32 v51, v51, v154, v63
	v_max3_f32 v51, v51, v155, v65
	v_max3_f32 v18, v51, v156, v157
	v_max3_f32 v18, v18, v158, v159
	v_max3_f32 v18, v18, v160, v161
	v_max3_f32 v18, v18, v162, v163
	v_max3_f32 v18, v18, v164, v165
	v_max3_f32 v18, v18, v166, v167
	v_cndmask_b32_e64 v77, v31, v245, s[80:81]
	v_max3_f32 v18, v18, v168, v77
	v_cndmask_b32_e64 v76, v32, v245, s[80:81]
	v_cndmask_b32_e64 v74, v33, v245, s[80:81]
	v_max3_f32 v18, v18, v76, v74
	v_cndmask_b32_e64 v73, v2, v245, s[80:81]
	v_cndmask_b32_e64 v66, v3, v245, s[80:81]
	v_max3_f32 v2, v18, v73, v66
	v_max3_f32 v2, v2, v64, v61
	v_max3_f32 v2, v2, v58, v57
	v_cndmask_b32_e64 v55, v8, v245, s[80:81]
	v_cndmask_b32_e64 v53, v9, v245, s[80:81]
	v_max3_f32 v2, v2, v55, v53
	v_cndmask_b32_e64 v52, v10, v245, s[80:81]
	v_cndmask_b32_e64 v33, v11, v245, s[80:81]
	v_max3_f32 v2, v2, v52, v33
	v_cndmask_b32_e64 v32, v12, v245, s[80:81]
	v_cndmask_b32_e64 v31, v13, v245, s[80:81]
	v_max3_f32 v2, v2, v32, v31
	v_max3_f32 v2, v2, v30, v29
	v_max3_f32 v2, v2, v28, v27
	v_cndmask_b32_e64 v26, v34, v245, s[12:13]
	v_cndmask_b32_e64 v25, v245, v35, s[46:47]
	v_max3_f32 v2, v2, v26, v25
	v_cndmask_b32_e64 v24, v36, v245, s[16:17]
	v_cndmask_b32_e64 v23, v37, v245, s[18:19]
	v_max3_f32 v2, v2, v24, v23
	v_cndmask_b32_e64 v22, v38, v245, s[20:21]
	v_cndmask_b32_e64 v21, v39, v245, s[22:23]
	v_max3_f32 v2, v2, v22, v21
	v_cndmask_b32_e64 v20, v40, v245, s[24:25]
	v_cndmask_b32_e64 v19, v41, v245, s[26:27]
	v_max3_f32 v2, v2, v20, v19
	v_cndmask_b32_e64 v18, v42, v245, s[28:29]
	v_cndmask_b32_e64 v17, v43, v245, s[30:31]
	v_max3_f32 v2, v2, v18, v17
	v_cndmask_b32_e64 v16, v44, v245, s[34:35]
	v_cndmask_b32_e64 v15, v45, v245, s[36:37]
	v_max3_f32 v2, v2, v16, v15
	v_cndmask_b32_e64 v14, v46, v245, s[38:39]
	v_cndmask_b32_e64 v13, v47, v245, s[42:43]
	v_max3_f32 v2, v2, v14, v13
	v_cndmask_b32_e64 v12, v48, v245, s[44:45]
	v_cndmask_b32_e64 v11, v49, v245, s[0:1]
	v_max3_f32 v2, v2, v12, v11
	ds_bpermute_b32 v3, v129, v2
	s_waitcnt lgkmcnt(0)
	v_max_f32_e32 v3, v3, v3
	v_max_f32_e32 v10, v2, v3
	v_sub_f32_e32 v2, v98, v10
	v_exp_f32_e32 v2, v2
	v_sub_f32_e32 v3, v67, v10
	v_exp_f32_e32 v3, v3
	v_sub_f32_e32 v35, v100, v10
	v_add_f32_e32 v4, 0, v2
	v_exp_f32_e32 v35, v35
	v_add_f32_e32 v5, v3, v4
	v_sub_f32_e32 v4, v68, v10
	v_exp_f32_e32 v4, v4
	v_sub_f32_e32 v36, v75, v10
	v_exp_f32_e32 v36, v36
	v_sub_f32_e32 v37, v101, v10
	v_add_f32_e32 v6, v4, v5
	v_sub_f32_e32 v5, v69, v10
	v_exp_f32_e32 v5, v5
	v_exp_f32_e32 v38, v37
	v_sub_f32_e32 v37, v102, v10
	v_exp_f32_e32 v39, v37
	v_add_f32_e32 v7, v5, v6
	v_sub_f32_e32 v6, v70, v10
	v_exp_f32_e32 v6, v6
	v_sub_f32_e32 v37, v78, v10
	v_exp_f32_e32 v40, v37
	v_sub_f32_e32 v37, v79, v10
	v_add_f32_e32 v8, v6, v7
	v_sub_f32_e32 v7, v71, v10
	v_exp_f32_e32 v7, v7
	v_exp_f32_e32 v45, v37
	v_sub_f32_e32 v37, v80, v10
	v_exp_f32_e32 v48, v37
	v_add_f32_e32 v9, v7, v8
	v_sub_f32_e32 v8, v72, v10
	v_exp_f32_e32 v8, v8
	v_sub_f32_e32 v37, v81, v10
	v_exp_f32_e32 v51, v37
	v_sub_f32_e32 v37, v50, v10
	v_add_f32_e32 v34, v8, v9
	v_sub_f32_e32 v9, v99, v10
	v_exp_f32_e32 v9, v9
	v_exp_f32_e32 v37, v37
	v_sub_f32_e32 v41, v103, v10
	v_exp_f32_e32 v41, v41
	v_add_f32_e32 v34, v9, v34
	v_add_f32_e32 v34, v35, v34
	v_add_f32_e32 v34, v36, v34
	v_add_f32_e32 v34, v38, v34
	v_add_f32_e32 v34, v39, v34
	v_add_f32_e32 v34, v40, v34
	v_add_f32_e32 v34, v45, v34
	v_sub_f32_e32 v42, v104, v10
	v_add_f32_e32 v34, v48, v34
	v_exp_f32_e32 v43, v42
	v_sub_f32_e32 v42, v105, v10
	v_add_f32_e32 v34, v51, v34
	v_exp_f32_e32 v44, v42
	v_sub_f32_e32 v42, v54, v10
	v_add_f32_e32 v34, v37, v34
	v_exp_f32_e32 v47, v42
	v_sub_f32_e32 v42, v106, v10
	v_add_f32_e32 v34, v41, v34
	v_exp_f32_e32 v56, v42
	v_sub_f32_e32 v42, v107, v10
	v_add_f32_e32 v34, v43, v34
	v_exp_f32_e32 v62, v42
	v_sub_f32_e32 v42, v108, v10
	v_add_f32_e32 v34, v44, v34
	v_exp_f32_e32 v67, v42
	v_sub_f32_e32 v42, v109, v10
	v_add_f32_e32 v34, v47, v34
	v_exp_f32_e32 v42, v42
	v_sub_f32_e32 v46, v59, v10
	v_add_f32_e32 v34, v56, v34
	v_exp_f32_e32 v46, v46
	v_sub_f32_e32 v49, v60, v10
	v_add_f32_e32 v34, v62, v34
	v_exp_f32_e32 v50, v49
	v_sub_f32_e32 v49, v153, v10
	v_add_f32_e32 v34, v67, v34
	v_exp_f32_e32 v54, v49
	v_sub_f32_e32 v49, v154, v10
	v_add_f32_e32 v34, v42, v34
	v_exp_f32_e32 v59, v49
	v_sub_f32_e32 v49, v63, v10
	v_add_f32_e32 v34, v46, v34
	v_exp_f32_e32 v69, v49
	v_sub_f32_e32 v49, v155, v10
	v_add_f32_e32 v34, v50, v34
	v_exp_f32_e32 v72, v49
	v_sub_f32_e32 v49, v65, v10
	v_add_f32_e32 v34, v54, v34
	v_exp_f32_e32 v78, v49
	v_sub_f32_e32 v49, v156, v10
	v_add_f32_e32 v34, v59, v34
	v_exp_f32_e32 v49, v49
	v_sub_f32_e32 v60, v157, v10
	v_add_f32_e32 v34, v69, v34
	v_exp_f32_e32 v60, v60
	v_sub_f32_e32 v63, v158, v10
	v_add_f32_e32 v34, v72, v34
	v_exp_f32_e32 v65, v63
	v_sub_f32_e32 v63, v159, v10
	v_add_f32_e32 v34, v78, v34
	v_exp_f32_e32 v68, v63
	v_sub_f32_e32 v63, v160, v10
	v_add_f32_e32 v34, v49, v34
	v_exp_f32_e32 v71, v63
	v_sub_f32_e32 v63, v161, v10
	v_add_f32_e32 v34, v60, v34
	v_exp_f32_e32 v98, v63
	v_sub_f32_e32 v63, v162, v10
	v_add_f32_e32 v34, v65, v34
	v_exp_f32_e32 v103, v63
	v_sub_f32_e32 v63, v163, v10
	v_add_f32_e32 v34, v68, v34
	v_exp_f32_e32 v104, v63
	v_sub_f32_e32 v63, v164, v10
	v_add_f32_e32 v34, v71, v34
	v_exp_f32_e32 v63, v63
	v_sub_f32_e32 v70, v165, v10
	v_add_f32_e32 v34, v98, v34
	v_exp_f32_e32 v70, v70
	v_sub_f32_e32 v75, v166, v10
	v_add_f32_e32 v34, v103, v34
	v_exp_f32_e32 v75, v75
	v_sub_f32_e32 v79, v167, v10
	v_add_f32_e32 v34, v104, v34
	v_exp_f32_e32 v80, v79
	v_sub_f32_e32 v79, v168, v10
	v_add_f32_e32 v34, v63, v34
	v_exp_f32_e32 v101, v79
	v_sub_f32_e32 v77, v77, v10
	v_add_f32_e32 v34, v70, v34
	v_exp_f32_e32 v155, v77
	v_sub_f32_e32 v76, v76, v10
	v_add_f32_e32 v34, v75, v34
	v_exp_f32_e32 v159, v76
	v_sub_f32_e32 v74, v74, v10
	v_add_f32_e32 v34, v80, v34
	v_exp_f32_e32 v163, v74
	v_sub_f32_e32 v73, v73, v10
	v_add_f32_e32 v34, v101, v34
	v_exp_f32_e32 v74, v73
	v_sub_f32_e32 v66, v66, v10
	v_add_f32_e32 v34, v155, v34
	v_exp_f32_e32 v102, v66
	v_sub_f32_e32 v64, v64, v10
	v_add_f32_e32 v34, v159, v34
	v_exp_f32_e32 v153, v64
	v_sub_f32_e32 v61, v61, v10
	v_add_f32_e32 v34, v163, v34
	v_exp_f32_e32 v154, v61
	v_sub_f32_e32 v58, v58, v10
	v_add_f32_e32 v34, v74, v34
	v_exp_f32_e32 v157, v58
	v_sub_f32_e32 v57, v57, v10
	v_add_f32_e32 v34, v102, v34
	v_exp_f32_e32 v166, v57
	v_sub_f32_e32 v55, v55, v10
	v_add_f32_e32 v34, v153, v34
	v_exp_f32_e32 v167, v55
	v_sub_f32_e32 v53, v53, v10
	v_add_f32_e32 v34, v154, v34
	v_exp_f32_e32 v168, v53
	v_sub_f32_e32 v52, v52, v10
	v_add_f32_e32 v34, v157, v34
	v_exp_f32_e32 v109, v52
	v_sub_f32_e32 v33, v33, v10
	v_add_f32_e32 v34, v166, v34
	v_exp_f32_e32 v156, v33
	v_sub_f32_e32 v32, v32, v10
	v_add_f32_e32 v34, v167, v34
	v_exp_f32_e32 v158, v32
	v_sub_f32_e32 v31, v31, v10
	v_add_f32_e32 v34, v168, v34
	v_exp_f32_e32 v160, v31
	v_sub_f32_e32 v30, v30, v10
	v_add_f32_e32 v34, v109, v34
	v_exp_f32_e32 v161, v30
	v_sub_f32_e32 v29, v29, v10
	v_add_f32_e32 v33, v156, v34
	v_exp_f32_e32 v162, v29
	v_sub_f32_e32 v28, v28, v10
	v_add_f32_e32 v32, v158, v33
	v_exp_f32_e32 v164, v28
	v_sub_f32_e32 v27, v27, v10
	v_add_f32_e32 v31, v160, v32
	v_exp_f32_e32 v165, v27
	v_sub_f32_e32 v26, v26, v10
	v_add_f32_e32 v30, v161, v31
	v_exp_f32_e32 v73, v26
	v_sub_f32_e32 v25, v25, v10
	v_add_f32_e32 v29, v162, v30
	v_exp_f32_e32 v76, v25
	v_sub_f32_e32 v24, v24, v10
	v_add_f32_e32 v28, v164, v29
	v_exp_f32_e32 v77, v24
	v_sub_f32_e32 v23, v23, v10
	v_add_f32_e32 v27, v165, v28
	v_exp_f32_e32 v79, v23
	v_sub_f32_e32 v22, v22, v10
	v_add_f32_e32 v26, v73, v27
	v_exp_f32_e32 v81, v22
	v_sub_f32_e32 v21, v21, v10
	v_add_f32_e32 v25, v76, v26
	v_exp_f32_e32 v99, v21
	v_sub_f32_e32 v20, v20, v10
	v_add_f32_e32 v24, v77, v25
	v_exp_f32_e32 v100, v20
	v_sub_f32_e32 v19, v19, v10
	v_add_u32_e32 v105, v130, v131
	v_add_f32_e32 v23, v79, v24
	v_exp_f32_e32 v108, v19
	v_sub_f32_e32 v18, v18, v10
	v_cvt_pk_bf16_f32 v2, v2, v3
	v_cvt_pk_bf16_f32 v3, v4, v5
	v_cvt_pk_bf16_f32 v4, v6, v7
	v_cvt_pk_bf16_f32 v5, v8, v9
	ds_read_b128 v[6:9], v105 offset:36864
	v_add_f32_e32 v22, v81, v23
	v_exp_f32_e32 v52, v18
	v_sub_f32_e32 v17, v17, v10
	v_add_f32_e32 v21, v99, v22
	v_exp_f32_e32 v53, v17
	v_sub_f32_e32 v16, v16, v10
	v_add_f32_e32 v20, v100, v21
	v_exp_f32_e32 v55, v16
	v_sub_f32_e32 v15, v15, v10
	v_add_f32_e32 v19, v108, v20
	v_exp_f32_e32 v57, v15
	v_sub_f32_e32 v14, v14, v10
	v_add_f32_e32 v18, v52, v19
	v_exp_f32_e32 v58, v14
	v_sub_f32_e32 v13, v13, v10
	v_add_f32_e32 v17, v53, v18
	v_exp_f32_e32 v61, v13
	v_sub_f32_e32 v12, v12, v10
	v_add_f32_e32 v16, v55, v17
	v_exp_f32_e32 v64, v12
	v_sub_f32_e32 v11, v11, v10
	v_add_f32_e32 v15, v57, v16
	v_exp_f32_e32 v66, v11
	v_add_u32_e32 v106, v130, v132
	v_add_f32_e32 v14, v58, v15
	s_waitcnt lgkmcnt(0)
	v_mfma_f32_32x32x16_bf16 v[18:33], v[6:9], v[2:5], 0
	ds_read_b128 v[6:9], v106 offset:36864
	v_cvt_pk_bf16_f32 v170, v35, v36
	v_cvt_pk_bf16_f32 v171, v38, v39
	v_cvt_pk_bf16_f32 v172, v40, v45
	v_cvt_pk_bf16_f32 v173, v48, v51
	ds_read_b128 v[174:177], v105 offset:36896
	v_add_f32_e32 v13, v61, v14
	v_add_f32_e32 v12, v64, v13
	v_add_f32_e32 v11, v66, v12
	ds_bpermute_b32 v12, v129, v11
	v_fma_f32 v10, v149, s94, -v10
	v_exp_f32_e32 v10, v10
	s_waitcnt lgkmcnt(1)
	v_mfma_f32_32x32x16_bf16 v[18:33], v[174:177], v[170:173], v[18:33]
	s_waitcnt lgkmcnt(0)
	v_add_f32_e32 v11, v11, v12
	ds_read_b128 v[174:177], v106 offset:36896
	v_add_f32_e32 v34, v10, v11
	v_add_u32_e32 v107, v133, v131
	v_cvt_pk_bf16_f32 v36, v37, v41
	v_cvt_pk_bf16_f32 v37, v43, v44
	v_cvt_pk_bf16_f32 v38, v47, v56
	v_mfma_f32_32x32x16_bf16 v[2:17], v[6:9], v[2:5], 0
	v_cvt_pk_bf16_f32 v39, v62, v67
	v_add_u32_e32 v106, v133, v132
	v_add_u32_e32 v105, v134, v131
	v_div_scale_f32 v35, vcc, v34, v34, 1.0
	s_waitcnt lgkmcnt(0)
	v_mfma_f32_32x32x16_bf16 v[2:17], v[174:177], v[170:173], v[2:17]
	ds_read_b128 v[170:173], v107 offset:36864
	s_waitcnt lgkmcnt(0)
	v_mfma_f32_32x32x16_bf16 v[18:33], v[170:173], v[36:39], v[18:33]
	ds_read_b128 v[170:173], v106 offset:36864
	s_waitcnt lgkmcnt(0)
	v_mfma_f32_32x32x16_bf16 v[2:17], v[170:173], v[36:39], v[2:17]
	v_cvt_pk_bf16_f32 v36, v42, v46
	v_cvt_pk_bf16_f32 v37, v50, v54
	v_cvt_pk_bf16_f32 v38, v59, v69
	v_cvt_pk_bf16_f32 v39, v72, v78
	ds_read_b128 v[40:43], v107 offset:36896
	s_waitcnt lgkmcnt(0)
	v_mfma_f32_32x32x16_bf16 v[18:33], v[40:43], v[36:39], v[18:33]
	ds_read_b128 v[40:43], v106 offset:36896
	s_waitcnt lgkmcnt(0)
	v_mfma_f32_32x32x16_bf16 v[2:17], v[40:43], v[36:39], v[2:17]
	v_cvt_pk_bf16_f32 v36, v49, v60
	v_cvt_pk_bf16_f32 v37, v65, v68
	v_cvt_pk_bf16_f32 v38, v71, v98
	v_cvt_pk_bf16_f32 v39, v103, v104
	ds_read_b128 v[40:43], v105 offset:36864
	v_add_u32_e32 v104, v134, v132
	v_add_u32_e32 v103, v135, v131
	s_waitcnt lgkmcnt(0)
	v_mfma_f32_32x32x16_bf16 v[18:33], v[40:43], v[36:39], v[18:33]
	ds_read_b128 v[40:43], v104 offset:36864
	v_or_b32_e32 v98, s88, v152
	s_waitcnt lgkmcnt(0)
	v_mfma_f32_32x32x16_bf16 v[2:17], v[40:43], v[36:39], v[2:17]
	v_cvt_pk_bf16_f32 v36, v63, v70
	v_cvt_pk_bf16_f32 v37, v75, v80
	v_cvt_pk_bf16_f32 v38, v101, v155
	v_cvt_pk_bf16_f32 v39, v159, v163
	ds_read_b128 v[40:43], v105 offset:36896
	v_add_u32_e32 v101, v136, v131
	s_waitcnt lgkmcnt(0)
	v_mfma_f32_32x32x16_bf16 v[18:33], v[40:43], v[36:39], v[18:33]
	ds_read_b128 v[40:43], v104 offset:36896
	s_waitcnt lgkmcnt(0)
	v_mfma_f32_32x32x16_bf16 v[2:17], v[40:43], v[36:39], v[2:17]
	v_cvt_pk_bf16_f32 v36, v74, v102
	v_cvt_pk_bf16_f32 v37, v153, v154
	v_cvt_pk_bf16_f32 v38, v157, v166
	v_cvt_pk_bf16_f32 v39, v167, v168
	ds_read_b128 v[40:43], v103 offset:36864
	v_add_u32_e32 v102, v135, v132
	s_waitcnt lgkmcnt(0)
	v_mfma_f32_32x32x16_bf16 v[18:33], v[40:43], v[36:39], v[18:33]
	ds_read_b128 v[40:43], v102 offset:36864
	s_waitcnt lgkmcnt(0)
	v_mfma_f32_32x32x16_bf16 v[2:17], v[40:43], v[36:39], v[2:17]
	v_cvt_pk_bf16_f32 v36, v109, v156
	v_cvt_pk_bf16_f32 v37, v158, v160
	v_cvt_pk_bf16_f32 v38, v161, v162
	v_cvt_pk_bf16_f32 v39, v164, v165
	ds_read_b128 v[40:43], v103 offset:36896
	s_waitcnt lgkmcnt(0)
	v_mfma_f32_32x32x16_bf16 v[18:33], v[40:43], v[36:39], v[18:33]
	ds_read_b128 v[40:43], v102 offset:36896
	s_waitcnt lgkmcnt(0)
	v_mfma_f32_32x32x16_bf16 v[2:17], v[40:43], v[36:39], v[2:17]
	v_cvt_pk_bf16_f32 v36, v73, v76
	v_cvt_pk_bf16_f32 v37, v77, v79
	v_cvt_pk_bf16_f32 v38, v81, v99
	v_cvt_pk_bf16_f32 v39, v100, v108
	ds_read_b128 v[40:43], v101 offset:36864
	v_add_u32_e32 v100, v136, v132
	v_mov_b32_e32 v99, s89
	s_waitcnt lgkmcnt(0)
	v_mfma_f32_32x32x16_bf16 v[18:33], v[40:43], v[36:39], v[18:33]
	ds_read_b128 v[40:43], v100 offset:36864
	s_waitcnt lgkmcnt(0)
	v_mfma_f32_32x32x16_bf16 v[2:17], v[40:43], v[36:39], v[2:17]
	v_cvt_pk_bf16_f32 v36, v52, v53
	v_cvt_pk_bf16_f32 v37, v55, v57
	v_cvt_pk_bf16_f32 v38, v58, v61
	v_cvt_pk_bf16_f32 v39, v64, v66
	ds_read_b128 v[40:43], v101 offset:36896
	s_waitcnt lgkmcnt(0)
	v_mfma_f32_32x32x16_bf16 v[18:33], v[40:43], v[36:39], v[18:33]
	ds_read_b128 v[40:43], v100 offset:36896
	s_waitcnt lgkmcnt(0)
	v_mfma_f32_32x32x16_bf16 v[2:17], v[40:43], v[36:39], v[2:17]
	v_rcp_f32_e32 v36, v35
	s_nop 0
	v_fma_f32 v37, -v35, v36, 1.0
	v_fmac_f32_e32 v36, v37, v36
	v_div_scale_f32 v37, vcc, 1.0, v34, 1.0
	v_mul_f32_e32 v38, v37, v36
	v_fma_f32 v39, -v35, v38, v37
	v_fmac_f32_e32 v38, v39, v36
	v_fma_f32 v35, -v35, v38, v37
	v_div_fmas_f32 v35, v35, v36, v38
	v_div_fixup_f32 v36, v35, v34, 1.0
	v_mul_f32_e32 v18, v18, v36
	v_mul_f32_e32 v19, v19, v36
	v_lshlrev_b64 v[34:35], 11, v[98:99]
	v_cvt_pk_bf16_f32 v18, v18, v19
	v_mul_f32_e32 v19, v20, v36
	v_lshl_add_u64 v[34:35], v[126:127], 0, v[34:35]
	v_mul_f32_e32 v20, v21, v36
	v_cvt_pk_bf16_f32 v19, v19, v20
	global_store_dwordx2 v[34:35], v[18:19], off
	v_mul_f32_e32 v18, v22, v36
	v_mul_f32_e32 v19, v23, v36
	v_cvt_pk_bf16_f32 v18, v18, v19
	v_mul_f32_e32 v19, v24, v36
	v_mul_f32_e32 v20, v25, v36
	v_cvt_pk_bf16_f32 v19, v19, v20
	global_store_dwordx2 v[34:35], v[18:19], off offset:16
	v_mul_f32_e32 v18, v26, v36
	v_mul_f32_e32 v19, v27, v36
	v_cvt_pk_bf16_f32 v18, v18, v19
	v_mul_f32_e32 v19, v28, v36
	v_mul_f32_e32 v20, v29, v36
	v_cvt_pk_bf16_f32 v19, v19, v20
	global_store_dwordx2 v[34:35], v[18:19], off offset:32
	v_mul_f32_e32 v18, v30, v36
	v_mul_f32_e32 v19, v31, v36
	v_cvt_pk_bf16_f32 v18, v18, v19
	v_mul_f32_e32 v19, v32, v36
	v_mul_f32_e32 v2, v2, v36
	v_mul_f32_e32 v3, v3, v36
	v_mul_f32_e32 v20, v33, v36
	v_cvt_pk_bf16_f32 v19, v19, v20
	global_store_dwordx2 v[34:35], v[18:19], off offset:48
	v_cvt_pk_bf16_f32 v2, v2, v3
	v_mul_f32_e32 v3, v4, v36
	v_mul_f32_e32 v4, v5, v36
	v_cvt_pk_bf16_f32 v3, v3, v4
	global_store_dwordx2 v[34:35], v[2:3], off offset:64
	v_mul_f32_e32 v2, v6, v36
	v_mul_f32_e32 v3, v7, v36
	v_cvt_pk_bf16_f32 v2, v2, v3
	v_mul_f32_e32 v3, v8, v36
	v_mul_f32_e32 v4, v9, v36
	v_cvt_pk_bf16_f32 v3, v3, v4
	global_store_dwordx2 v[34:35], v[2:3], off offset:80
	v_mul_f32_e32 v2, v10, v36
	v_mul_f32_e32 v3, v11, v36
	v_cvt_pk_bf16_f32 v2, v2, v3
	v_mul_f32_e32 v3, v12, v36
	v_mul_f32_e32 v4, v13, v36
	v_cvt_pk_bf16_f32 v3, v3, v4
	global_store_dwordx2 v[34:35], v[2:3], off offset:96
	v_mul_f32_e32 v2, v14, v36
	v_mul_f32_e32 v3, v15, v36
	v_cvt_pk_bf16_f32 v2, v2, v3
	v_mul_f32_e32 v3, v16, v36
	v_mul_f32_e32 v4, v17, v36
	v_cvt_pk_bf16_f32 v3, v3, v4
	global_store_dwordx2 v[34:35], v[2:3], off offset:112
	ds_read_b128 v[2:5], v143
	ds_read_b128 v[6:9], v143 offset:32
	s_waitcnt lgkmcnt(1)
	v_mfma_f32_32x32x16_bf16 v[66:81], v[2:5], v[94:97], 0
	ds_read_b128 v[2:5], v143 offset:64
	v_or_b32_e32 v98, s87, v150
	v_or_b32_e32 v98, s88, v98
	s_waitcnt lgkmcnt(1)
	v_mfma_f32_32x32x16_bf16 v[66:81], v[6:9], v[90:93], v[66:81]
	s_waitcnt lgkmcnt(0)
	v_mfma_f32_32x32x16_bf16 v[66:81], v[2:5], v[86:89], v[66:81]
	ds_read_b128 v[2:5], v143 offset:96
	s_waitcnt lgkmcnt(0)
	v_mfma_f32_32x32x16_bf16 v[66:81], v[2:5], v[82:85], v[66:81]
	ds_read_b128 v[2:5], v144
	ds_read_b128 v[6:9], v144 offset:32
	s_waitcnt lgkmcnt(1)
	v_mfma_f32_32x32x16_bf16 v[34:49], v[2:5], v[94:97], 0
	ds_read_b128 v[2:5], v144 offset:64
	s_nop 6
	v_cndmask_b32_e64 v66, v245, v66, s[48:49]
	v_cndmask_b32_e64 v68, v245, v68, s[52:53]
	v_cndmask_b32_e64 v69, v245, v69, s[54:55]
	v_cndmask_b32_e64 v70, v245, v70, s[56:57]
	v_cndmask_b32_e64 v71, v245, v71, s[58:59]
	v_cndmask_b32_e64 v72, v245, v72, s[60:61]
	s_waitcnt lgkmcnt(1)
	v_mfma_f32_32x32x16_bf16 v[34:49], v[6:9], v[90:93], v[34:49]
	v_cndmask_b32_e64 v73, v245, v73, s[62:63]
	v_cndmask_b32_e64 v74, v245, v74, s[64:65]
	v_cndmask_b32_e64 v75, v245, v75, s[66:67]
	v_cndmask_b32_e64 v76, v245, v76, s[68:69]
	v_cndmask_b32_e64 v77, v245, v77, s[70:71]
	v_cndmask_b32_e64 v78, v245, v78, s[72:73]
	v_cndmask_b32_e64 v79, v245, v79, s[74:75]
	s_waitcnt lgkmcnt(0)
	v_mfma_f32_32x32x16_bf16 v[34:49], v[2:5], v[86:89], v[34:49]
	ds_read_b128 v[2:5], v144 offset:96
	v_cndmask_b32_e64 v80, v245, v80, s[76:77]
	v_cndmask_b32_e64 v81, v245, v81, s[78:79]
	s_waitcnt lgkmcnt(0)
	v_mfma_f32_32x32x16_bf16 v[34:49], v[2:5], v[82:85], v[34:49]
	ds_read_b128 v[2:5], v145
	ds_read_b128 v[6:9], v145 offset:32
	s_waitcnt lgkmcnt(1)
	v_mfma_f32_32x32x16_bf16 v[18:33], v[2:5], v[94:97], 0
	ds_read_b128 v[2:5], v145 offset:64
	s_nop 6
	v_cndmask_b32_e64 v42, v42, v245, s[80:81]
	s_waitcnt lgkmcnt(1)
	v_mfma_f32_32x32x16_bf16 v[18:33], v[6:9], v[90:93], v[18:33]
	s_waitcnt lgkmcnt(0)
	v_mfma_f32_32x32x16_bf16 v[18:33], v[2:5], v[86:89], v[18:33]
	ds_read_b128 v[2:5], v145 offset:96
	s_waitcnt lgkmcnt(0)
	v_mfma_f32_32x32x16_bf16 v[18:33], v[2:5], v[82:85], v[18:33]
	ds_read_b128 v[2:5], v146
	ds_read_b128 v[50:53], v146 offset:32
	s_waitcnt lgkmcnt(1)
	v_mfma_f32_32x32x16_bf16 v[2:17], v[2:5], v[94:97], 0
	s_nop 7
	v_cndmask_b32_e64 v108, v18, v245, s[80:81]
	v_cndmask_b32_e64 v109, v19, v245, s[80:81]
	v_cndmask_b32_e64 v150, v20, v245, s[80:81]
	v_cndmask_b32_e64 v156, v26, v245, s[80:81]
	v_cndmask_b32_e64 v157, v27, v245, s[80:81]
	v_cndmask_b32_e64 v158, v28, v245, s[80:81]
	v_cndmask_b32_e64 v159, v29, v245, s[80:81]
	s_waitcnt lgkmcnt(0)
	v_mfma_f32_32x32x16_bf16 v[2:17], v[50:53], v[90:93], v[2:17]
	ds_read_b128 v[50:53], v146 offset:64
	v_cndmask_b32_e64 v160, v30, v245, s[80:81]
	v_cndmask_b32_e64 v161, v31, v245, s[80:81]
	v_cndmask_b32_e64 v162, v32, v245, s[80:81]
	v_cndmask_b32_e64 v163, v33, v245, s[80:81]
	s_waitcnt lgkmcnt(0)
	v_mfma_f32_32x32x16_bf16 v[2:17], v[50:53], v[86:89], v[2:17]
	ds_read_b128 v[50:53], v146 offset:96
	s_waitcnt lgkmcnt(0)
	v_mfma_f32_32x32x16_bf16 v[2:17], v[50:53], v[82:85], v[2:17]
	ds_read_b128 v[50:53], v147
	ds_read_b128 v[152:155], v147 offset:32
	s_waitcnt lgkmcnt(1)
	v_mfma_f32_32x32x16_bf16 v[50:65], v[50:53], v[94:97], 0
	v_cndmask_b32_e64 v94, v46, v245, s[80:81]
	v_cndmask_b32_e64 v95, v47, v245, s[80:81]
	v_cndmask_b32_e64 v96, v48, v245, s[80:81]
	v_cndmask_b32_e64 v97, v49, v245, s[80:81]
	s_waitcnt lgkmcnt(0)
	v_mfma_f32_32x32x16_bf16 v[50:65], v[152:155], v[90:93], v[50:65]
	ds_read_b128 v[90:93], v147 offset:64
	v_cndmask_b32_e64 v152, v22, v245, s[80:81]
	v_cndmask_b32_e64 v153, v23, v245, s[80:81]
	v_cndmask_b32_e64 v154, v24, v245, s[80:81]
	v_cndmask_b32_e64 v155, v25, v245, s[80:81]
	s_waitcnt lgkmcnt(0)
	v_mfma_f32_32x32x16_bf16 v[50:65], v[90:93], v[86:89], v[50:65]
	ds_read_b128 v[86:89], v147 offset:96
	v_cndmask_b32_e64 v90, v41, v245, s[80:81]
	v_cndmask_b32_e64 v91, v43, v245, s[80:81]
	v_cndmask_b32_e64 v92, v44, v245, s[80:81]
	v_cndmask_b32_e64 v93, v45, v245, s[80:81]
	s_waitcnt lgkmcnt(0)
	v_mfma_f32_32x32x16_bf16 v[50:65], v[86:89], v[82:85], v[50:65]
	v_cndmask_b32_e64 v82, v245, v67, s[50:51]
	v_max3_f32 v67, v151, v66, v82
	v_max3_f32 v67, v67, v68, v69
	v_max3_f32 v67, v67, v70, v71
	v_max3_f32 v67, v67, v72, v73
	v_max3_f32 v67, v67, v74, v75
	v_max3_f32 v67, v67, v76, v77
	v_max3_f32 v67, v67, v78, v79
	v_max3_f32 v67, v67, v80, v81
	v_cndmask_b32_e64 v83, v34, v245, s[80:81]
	v_cndmask_b32_e64 v84, v35, v245, s[80:81]
	v_max3_f32 v34, v67, v83, v84
	v_cndmask_b32_e64 v85, v36, v245, s[80:81]
	v_cndmask_b32_e64 v86, v37, v245, s[80:81]
	v_max3_f32 v34, v34, v85, v86
	v_cndmask_b32_e64 v87, v38, v245, s[80:81]
	v_cndmask_b32_e64 v88, v39, v245, s[80:81]
	v_max3_f32 v34, v34, v87, v88
	v_cndmask_b32_e64 v89, v40, v245, s[80:81]
	v_max3_f32 v34, v34, v89, v90
	v_max3_f32 v34, v34, v42, v91
	v_max3_f32 v34, v34, v92, v93
	v_max3_f32 v34, v34, v94, v95
	v_max3_f32 v34, v34, v96, v97
	v_max3_f32 v18, v34, v108, v109
	v_cndmask_b32_e64 v151, v21, v245, s[80:81]
	v_max3_f32 v18, v18, v150, v151
	v_max3_f32 v18, v18, v152, v153
	v_max3_f32 v18, v18, v154, v155
	v_max3_f32 v18, v18, v156, v157
	v_max3_f32 v18, v18, v158, v159
	v_max3_f32 v18, v18, v160, v161
	v_max3_f32 v18, v18, v162, v163
	v_max3_f32 v18, v18, v2, v3
	v_max3_f32 v18, v18, v4, v5
	v_max3_f32 v18, v18, v6, v7
	v_max3_f32 v18, v18, v8, v9
	v_max3_f32 v18, v18, v10, v11
	v_max3_f32 v18, v18, v12, v13
	v_max3_f32 v18, v18, v14, v15
	v_max3_f32 v18, v18, v16, v17
	v_cndmask_b32_e64 v67, v50, v245, s[12:13]
	v_cndmask_b32_e64 v50, v245, v51, s[46:47]
	v_max3_f32 v18, v18, v67, v50
	v_cndmask_b32_e64 v49, v52, v245, s[16:17]
	v_cndmask_b32_e64 v48, v53, v245, s[18:19]
	v_max3_f32 v18, v18, v49, v48
	v_cndmask_b32_e64 v47, v54, v245, s[20:21]
	v_cndmask_b32_e64 v45, v55, v245, s[22:23]
	v_max3_f32 v18, v18, v47, v45
	v_cndmask_b32_e64 v43, v56, v245, s[24:25]
	v_cndmask_b32_e64 v40, v57, v245, s[26:27]
	v_max3_f32 v18, v18, v43, v40
	v_cndmask_b32_e64 v34, v58, v245, s[28:29]
	v_cndmask_b32_e64 v33, v59, v245, s[30:31]
	v_max3_f32 v18, v18, v34, v33
	v_cndmask_b32_e64 v32, v60, v245, s[34:35]
	v_cndmask_b32_e64 v31, v61, v245, s[36:37]
	v_max3_f32 v18, v18, v32, v31
	v_cndmask_b32_e64 v30, v62, v245, s[38:39]
	v_cndmask_b32_e64 v29, v63, v245, s[42:43]
	v_max3_f32 v18, v18, v30, v29
	v_cndmask_b32_e64 v28, v64, v245, s[44:45]
	v_cndmask_b32_e64 v27, v65, v245, s[0:1]
	v_max3_f32 v18, v18, v28, v27
	ds_bpermute_b32 v19, v129, v18
	s_waitcnt lgkmcnt(0)
	v_max_f32_e32 v19, v19, v19
	v_max_f32_e32 v26, v18, v19
	v_sub_f32_e32 v18, v66, v26
	v_exp_f32_e32 v18, v18
	v_sub_f32_e32 v19, v82, v26
	v_exp_f32_e32 v19, v19
	v_sub_f32_e32 v38, v76, v26
	v_add_f32_e32 v20, 0, v18
	v_exp_f32_e32 v38, v38
	v_add_f32_e32 v21, v19, v20
	v_sub_f32_e32 v20, v68, v26
	v_exp_f32_e32 v20, v20
	v_sub_f32_e32 v39, v77, v26
	v_exp_f32_e32 v39, v39
	v_sub_f32_e32 v41, v78, v26
	v_add_f32_e32 v22, v20, v21
	v_sub_f32_e32 v21, v69, v26
	v_exp_f32_e32 v21, v21
	v_exp_f32_e32 v44, v41
	v_sub_f32_e32 v41, v79, v26
	v_exp_f32_e32 v54, v41
	v_add_f32_e32 v23, v21, v22
	v_sub_f32_e32 v22, v70, v26
	v_exp_f32_e32 v22, v22
	v_sub_f32_e32 v41, v80, v26
	v_exp_f32_e32 v58, v41
	v_sub_f32_e32 v41, v81, v26
	v_add_f32_e32 v24, v22, v23
	v_sub_f32_e32 v23, v71, v26
	v_exp_f32_e32 v23, v23
	v_exp_f32_e32 v60, v41
	v_sub_f32_e32 v53, v87, v26
	v_exp_f32_e32 v56, v53
	v_add_f32_e32 v25, v23, v24
	v_sub_f32_e32 v24, v72, v26
	v_exp_f32_e32 v24, v24
	v_sub_f32_e32 v53, v88, v26
	v_exp_f32_e32 v63, v53
	v_sub_f32_e32 v53, v89, v26
	v_add_f32_e32 v35, v24, v25
	v_sub_f32_e32 v25, v73, v26
	v_exp_f32_e32 v25, v25
	v_exp_f32_e32 v70, v53
	v_sub_f32_e32 v53, v90, v26
	v_sub_f32_e32 v42, v42, v26
	v_add_f32_e32 v36, v25, v35
	v_sub_f32_e32 v35, v74, v26
	v_exp_f32_e32 v35, v35
	v_exp_f32_e32 v42, v42
	v_sub_f32_e32 v55, v92, v26
	v_exp_f32_e32 v57, v55
	v_add_f32_e32 v37, v35, v36
	v_sub_f32_e32 v36, v75, v26
	v_exp_f32_e32 v36, v36
	v_exp_f32_e32 v75, v53
	v_sub_f32_e32 v53, v91, v26
	v_exp_f32_e32 v53, v53
	v_add_f32_e32 v37, v36, v37
	v_add_f32_e32 v37, v38, v37
	v_add_f32_e32 v37, v39, v37
	v_add_f32_e32 v37, v44, v37
	v_add_f32_e32 v37, v54, v37
	v_add_f32_e32 v37, v58, v37
	v_add_f32_e32 v41, v60, v37
	v_sub_f32_e32 v37, v83, v26
	v_exp_f32_e32 v37, v37
	v_sub_f32_e32 v55, v93, v26
	v_exp_f32_e32 v59, v55
	v_sub_f32_e32 v55, v94, v26
	v_add_f32_e32 v46, v37, v41
	v_sub_f32_e32 v41, v84, v26
	v_exp_f32_e32 v41, v41
	v_exp_f32_e32 v66, v55
	v_sub_f32_e32 v55, v95, v26
	v_exp_f32_e32 v78, v55
	v_add_f32_e32 v51, v41, v46
	v_sub_f32_e32 v46, v85, v26
	v_exp_f32_e32 v46, v46
	v_sub_f32_e32 v55, v96, v26
	v_exp_f32_e32 v82, v55
	v_sub_f32_e32 v55, v97, v26
	v_add_f32_e32 v52, v46, v51
	v_sub_f32_e32 v51, v86, v26
	v_exp_f32_e32 v51, v51
	v_exp_f32_e32 v85, v55
	v_sub_f32_e32 v55, v108, v26
	v_exp_f32_e32 v55, v55
	v_add_f32_e32 v52, v51, v52
	v_add_f32_e32 v52, v56, v52
	v_add_f32_e32 v52, v63, v52
	v_add_f32_e32 v52, v70, v52
	v_add_f32_e32 v52, v75, v52
	v_add_f32_e32 v52, v42, v52
	v_add_f32_e32 v52, v53, v52
	v_add_f32_e32 v52, v57, v52
	v_add_f32_e32 v52, v59, v52
	v_add_f32_e32 v52, v66, v52
	v_sub_f32_e32 v61, v109, v26
	v_add_f32_e32 v52, v78, v52
	v_exp_f32_e32 v62, v61
	v_sub_f32_e32 v61, v150, v26
	v_add_f32_e32 v52, v82, v52
	v_exp_f32_e32 v68, v61
	v_sub_f32_e32 v61, v151, v26
	v_add_f32_e32 v52, v85, v52
	v_exp_f32_e32 v74, v61
	v_sub_f32_e32 v61, v152, v26
	v_add_f32_e32 v52, v55, v52
	v_exp_f32_e32 v80, v61
	v_sub_f32_e32 v61, v153, v26
	v_add_f32_e32 v52, v62, v52
	v_exp_f32_e32 v88, v61
	v_sub_f32_e32 v61, v154, v26
	v_add_f32_e32 v52, v68, v52
	v_exp_f32_e32 v94, v61
	v_sub_f32_e32 v61, v155, v26
	v_add_f32_e32 v52, v74, v52
	v_exp_f32_e32 v109, v61
	v_sub_f32_e32 v61, v156, v26
	v_add_f32_e32 v52, v80, v52
	v_exp_f32_e32 v64, v61
	v_sub_f32_e32 v61, v157, v26
	v_add_f32_e32 v52, v88, v52
	v_exp_f32_e32 v77, v61
	v_sub_f32_e32 v61, v158, v26
	v_add_f32_e32 v52, v94, v52
	v_exp_f32_e32 v81, v61
	v_sub_f32_e32 v61, v159, v26
	v_add_f32_e32 v52, v109, v52
	v_exp_f32_e32 v83, v61
	v_sub_f32_e32 v61, v160, v26
	v_add_f32_e32 v52, v64, v52
	v_exp_f32_e32 v90, v61
	v_sub_f32_e32 v61, v161, v26
	v_add_f32_e32 v52, v77, v52
	v_exp_f32_e32 v150, v61
	v_sub_f32_e32 v61, v162, v26
	v_add_f32_e32 v52, v81, v52
	v_exp_f32_e32 v152, v61
	v_sub_f32_e32 v61, v163, v26
	v_add_f32_e32 v52, v83, v52
	v_exp_f32_e32 v153, v61
	v_sub_f32_e32 v2, v2, v26
	v_add_f32_e32 v52, v90, v52
	v_exp_f32_e32 v79, v2
	v_sub_f32_e32 v3, v3, v26
	v_add_f32_e32 v52, v150, v52
	v_exp_f32_e32 v86, v3
	v_sub_f32_e32 v3, v4, v26
	v_add_f32_e32 v52, v152, v52
	v_exp_f32_e32 v92, v3
	v_sub_f32_e32 v3, v5, v26
	v_add_f32_e32 v52, v153, v52
	v_exp_f32_e32 v97, v3
	v_sub_f32_e32 v3, v6, v26
	v_add_f32_e32 v2, v79, v52
	v_exp_f32_e32 v151, v3
	v_sub_f32_e32 v3, v7, v26
	v_add_f32_e32 v2, v86, v2
	v_exp_f32_e32 v154, v3
	v_sub_f32_e32 v3, v8, v26
	v_add_f32_e32 v2, v92, v2
	v_exp_f32_e32 v155, v3
	v_sub_f32_e32 v3, v9, v26
	v_add_f32_e32 v2, v97, v2
	v_exp_f32_e32 v156, v3
	v_sub_f32_e32 v3, v10, v26
	v_add_f32_e32 v2, v151, v2
	v_exp_f32_e32 v84, v3
	v_sub_f32_e32 v3, v11, v26
	v_add_f32_e32 v2, v154, v2
	v_exp_f32_e32 v87, v3
	v_sub_f32_e32 v3, v12, v26
	v_add_f32_e32 v2, v155, v2
	v_exp_f32_e32 v89, v3
	v_sub_f32_e32 v3, v13, v26
	v_add_f32_e32 v2, v156, v2
	v_exp_f32_e32 v91, v3
	v_sub_f32_e32 v3, v14, v26
	v_add_f32_e32 v2, v84, v2
	v_exp_f32_e32 v93, v3
	v_sub_f32_e32 v3, v15, v26
	v_add_f32_e32 v2, v87, v2
	v_exp_f32_e32 v95, v3
	v_sub_f32_e32 v3, v16, v26
	v_add_f32_e32 v2, v89, v2
	v_exp_f32_e32 v96, v3
	v_sub_f32_e32 v3, v17, v26
	v_add_f32_e32 v2, v91, v2
	v_exp_f32_e32 v108, v3
	v_sub_f32_e32 v3, v67, v26
	v_add_f32_e32 v2, v93, v2
	v_exp_f32_e32 v61, v3
	v_sub_f32_e32 v3, v50, v26
	v_add_f32_e32 v2, v95, v2
	v_exp_f32_e32 v65, v3
	v_sub_f32_e32 v3, v49, v26
	v_add_f32_e32 v2, v96, v2
	v_exp_f32_e32 v67, v3
	v_sub_f32_e32 v3, v48, v26
	v_add_f32_e32 v2, v108, v2
	v_exp_f32_e32 v69, v3
	v_sub_f32_e32 v3, v47, v26
	v_add_f32_e32 v2, v61, v2
	v_exp_f32_e32 v71, v3
	v_sub_f32_e32 v3, v45, v26
	v_add_f32_e32 v2, v65, v2
	v_exp_f32_e32 v72, v3
	v_sub_f32_e32 v3, v43, v26
	v_add_f32_e32 v2, v67, v2
	v_exp_f32_e32 v73, v3
	v_sub_f32_e32 v3, v40, v26
	v_add_f32_e32 v2, v69, v2
	v_exp_f32_e32 v76, v3
	v_sub_f32_e32 v3, v34, v26
	v_add_f32_e32 v2, v71, v2
	v_exp_f32_e32 v40, v3
	v_sub_f32_e32 v3, v33, v26
	v_add_f32_e32 v2, v72, v2
	v_exp_f32_e32 v43, v3
	v_sub_f32_e32 v3, v32, v26
	v_add_f32_e32 v2, v73, v2
	v_exp_f32_e32 v45, v3
	v_sub_f32_e32 v3, v31, v26
	v_add_f32_e32 v2, v76, v2
	v_exp_f32_e32 v47, v3
	v_sub_f32_e32 v3, v30, v26
	v_add_f32_e32 v2, v40, v2
	v_exp_f32_e32 v48, v3
	v_sub_f32_e32 v3, v29, v26
	v_add_f32_e32 v2, v43, v2
	v_exp_f32_e32 v49, v3
	v_sub_f32_e32 v3, v28, v26
	v_add_f32_e32 v2, v45, v2
	v_exp_f32_e32 v50, v3
	v_sub_f32_e32 v3, v27, v26
	v_add_f32_e32 v2, v47, v2
	v_exp_f32_e32 v52, v3
	v_add_f32_e32 v2, v48, v2
	v_add_f32_e32 v2, v49, v2
	v_add_f32_e32 v2, v50, v2
	v_add_f32_e32 v2, v52, v2
	ds_bpermute_b32 v3, v129, v2
	s_waitcnt lgkmcnt(0)
	v_add_f32_e32 v2, v2, v3
	v_fma_f32 v3, v149, s94, -v26
	v_exp_f32_e32 v3, v3
	s_nop 0
	v_add_f32_e32 v34, v3, v2
	v_cvt_pk_bf16_f32 v2, v18, v19
	v_cvt_pk_bf16_f32 v3, v20, v21
	v_cvt_pk_bf16_f32 v4, v22, v23
	v_cvt_pk_bf16_f32 v5, v24, v25
	ds_read_b128 v[6:9], v107 offset:36864
	s_waitcnt lgkmcnt(0)
	v_mfma_f32_32x32x16_bf16 v[18:33], v[6:9], v[2:5], 0
	ds_read_b128 v[6:9], v106 offset:36864
	v_cvt_pk_bf16_f32 v158, v35, v36
	v_cvt_pk_bf16_f32 v159, v38, v39
	v_cvt_pk_bf16_f32 v160, v44, v54
	v_cvt_pk_bf16_f32 v161, v58, v60
	ds_read_b128 v[162:165], v107 offset:36896
	v_add_u32_e32 v35, v137, v131
	s_waitcnt lgkmcnt(0)
	v_mfma_f32_32x32x16_bf16 v[18:33], v[162:165], v[158:161], v[18:33]
	ds_read_b128 v[162:165], v106 offset:36896
	v_cvt_pk_bf16_f32 v36, v37, v41
	v_cvt_pk_bf16_f32 v37, v46, v51
	v_cvt_pk_bf16_f32 v38, v56, v63
	v_cvt_pk_bf16_f32 v39, v70, v75
	v_add_u32_e32 v44, v137, v132
	v_mfma_f32_32x32x16_bf16 v[2:17], v[6:9], v[2:5], 0
	s_waitcnt lgkmcnt(0)
	v_mfma_f32_32x32x16_bf16 v[2:17], v[162:165], v[158:161], v[2:17]
	ds_read_b128 v[158:161], v105 offset:36864
	s_waitcnt lgkmcnt(0)
	v_mfma_f32_32x32x16_bf16 v[18:33], v[158:161], v[36:39], v[18:33]
	ds_read_b128 v[158:161], v104 offset:36864
	s_waitcnt lgkmcnt(0)
	v_mfma_f32_32x32x16_bf16 v[2:17], v[158:161], v[36:39], v[2:17]
	v_cvt_pk_bf16_f32 v36, v42, v53
	v_cvt_pk_bf16_f32 v37, v57, v59
	v_cvt_pk_bf16_f32 v38, v66, v78
	v_cvt_pk_bf16_f32 v39, v82, v85
	ds_read_b128 v[56:59], v105 offset:36896
	s_waitcnt lgkmcnt(0)
	v_mfma_f32_32x32x16_bf16 v[18:33], v[56:59], v[36:39], v[18:33]
	ds_read_b128 v[56:59], v104 offset:36896
	s_waitcnt lgkmcnt(0)
	v_mfma_f32_32x32x16_bf16 v[2:17], v[56:59], v[36:39], v[2:17]
	v_cvt_pk_bf16_f32 v36, v55, v62
	v_cvt_pk_bf16_f32 v37, v68, v74
	v_cvt_pk_bf16_f32 v38, v80, v88
	v_cvt_pk_bf16_f32 v39, v94, v109
	ds_read_b128 v[54:57], v103 offset:36864
	s_waitcnt lgkmcnt(0)
	v_mfma_f32_32x32x16_bf16 v[18:33], v[54:57], v[36:39], v[18:33]
	ds_read_b128 v[54:57], v102 offset:36864
	s_waitcnt lgkmcnt(0)
	v_mfma_f32_32x32x16_bf16 v[2:17], v[54:57], v[36:39], v[2:17]
	v_cvt_pk_bf16_f32 v36, v64, v77
	v_cvt_pk_bf16_f32 v37, v81, v83
	v_cvt_pk_bf16_f32 v38, v90, v150
	v_cvt_pk_bf16_f32 v39, v152, v153
	ds_read_b128 v[54:57], v103 offset:36896
	s_waitcnt lgkmcnt(0)
	v_mfma_f32_32x32x16_bf16 v[18:33], v[54:57], v[36:39], v[18:33]
	ds_read_b128 v[54:57], v102 offset:36896
	s_waitcnt lgkmcnt(0)
	v_mfma_f32_32x32x16_bf16 v[2:17], v[54:57], v[36:39], v[2:17]
	v_cvt_pk_bf16_f32 v36, v79, v86
	v_cvt_pk_bf16_f32 v37, v92, v97
	v_cvt_pk_bf16_f32 v38, v151, v154
	v_cvt_pk_bf16_f32 v39, v155, v156
	ds_read_b128 v[54:57], v101 offset:36864
	s_waitcnt lgkmcnt(0)
	v_mfma_f32_32x32x16_bf16 v[18:33], v[54:57], v[36:39], v[18:33]
	ds_read_b128 v[54:57], v100 offset:36864
	s_waitcnt lgkmcnt(0)
	v_mfma_f32_32x32x16_bf16 v[2:17], v[54:57], v[36:39], v[2:17]
	v_cvt_pk_bf16_f32 v36, v84, v87
	v_cvt_pk_bf16_f32 v37, v89, v91
	v_cvt_pk_bf16_f32 v38, v93, v95
	v_cvt_pk_bf16_f32 v39, v96, v108
	ds_read_b128 v[54:57], v101 offset:36896
	s_waitcnt lgkmcnt(0)
	v_mfma_f32_32x32x16_bf16 v[18:33], v[54:57], v[36:39], v[18:33]
	ds_read_b128 v[54:57], v100 offset:36896
	s_waitcnt lgkmcnt(0)
	v_mfma_f32_32x32x16_bf16 v[2:17], v[54:57], v[36:39], v[2:17]
	v_cvt_pk_bf16_f32 v36, v61, v65
	v_cvt_pk_bf16_f32 v37, v67, v69
	v_cvt_pk_bf16_f32 v38, v71, v72
	v_cvt_pk_bf16_f32 v39, v73, v76
	ds_read_b128 v[54:57], v35 offset:36864
	s_waitcnt lgkmcnt(0)
	v_mfma_f32_32x32x16_bf16 v[18:33], v[54:57], v[36:39], v[18:33]
	ds_read_b128 v[54:57], v44 offset:36864
	s_waitcnt lgkmcnt(0)
	v_mfma_f32_32x32x16_bf16 v[2:17], v[54:57], v[36:39], v[2:17]
	v_cvt_pk_bf16_f32 v36, v40, v43
	v_cvt_pk_bf16_f32 v37, v45, v47
	v_cvt_pk_bf16_f32 v38, v48, v49
	v_cvt_pk_bf16_f32 v39, v50, v52
	ds_read_b128 v[40:43], v35 offset:36896
	v_div_scale_f32 v35, s[48:49], v34, v34, 1.0
	s_waitcnt lgkmcnt(0)
	v_mfma_f32_32x32x16_bf16 v[18:33], v[40:43], v[36:39], v[18:33]
	ds_read_b128 v[40:43], v44 offset:36896
	s_waitcnt lgkmcnt(0)
	v_mfma_f32_32x32x16_bf16 v[2:17], v[40:43], v[36:39], v[2:17]
	v_rcp_f32_e32 v36, v35
	s_nop 0
	v_fma_f32 v37, -v35, v36, 1.0
	v_fmac_f32_e32 v36, v37, v36
	v_div_scale_f32 v37, vcc, 1.0, v34, 1.0
	v_mul_f32_e32 v38, v37, v36
	v_fma_f32 v39, -v35, v38, v37
	v_fmac_f32_e32 v38, v39, v36
	v_fma_f32 v35, -v35, v38, v37
	v_div_fmas_f32 v35, v35, v36, v38
	v_div_fixup_f32 v36, v35, v34, 1.0
	v_mul_f32_e32 v18, v18, v36
	v_mul_f32_e32 v19, v19, v36
	v_lshlrev_b64 v[34:35], 11, v[98:99]
	v_cvt_pk_bf16_f32 v18, v18, v19
	v_mul_f32_e32 v19, v20, v36
	v_lshl_add_u64 v[34:35], v[126:127], 0, v[34:35]
	v_mul_f32_e32 v20, v21, v36
	v_cvt_pk_bf16_f32 v19, v19, v20
	global_store_dwordx2 v[34:35], v[18:19], off
	v_mul_f32_e32 v18, v22, v36
	v_mul_f32_e32 v19, v23, v36
	v_cvt_pk_bf16_f32 v18, v18, v19
	v_mul_f32_e32 v19, v24, v36
	v_mul_f32_e32 v20, v25, v36
	v_cvt_pk_bf16_f32 v19, v19, v20
	global_store_dwordx2 v[34:35], v[18:19], off offset:16
	v_mul_f32_e32 v18, v26, v36
	v_mul_f32_e32 v19, v27, v36
	v_cvt_pk_bf16_f32 v18, v18, v19
	v_mul_f32_e32 v19, v28, v36
	v_mul_f32_e32 v20, v29, v36
	v_cvt_pk_bf16_f32 v19, v19, v20
	global_store_dwordx2 v[34:35], v[18:19], off offset:32
	v_mul_f32_e32 v18, v30, v36
	v_mul_f32_e32 v19, v31, v36
	v_cvt_pk_bf16_f32 v18, v18, v19
	v_mul_f32_e32 v19, v32, v36
	v_mul_f32_e32 v2, v2, v36
	v_mul_f32_e32 v3, v3, v36
	v_mul_f32_e32 v20, v33, v36
	v_cvt_pk_bf16_f32 v19, v19, v20
	global_store_dwordx2 v[34:35], v[18:19], off offset:48
	v_cvt_pk_bf16_f32 v2, v2, v3
	v_mul_f32_e32 v3, v4, v36
	v_mul_f32_e32 v4, v5, v36
	v_cvt_pk_bf16_f32 v3, v3, v4
	global_store_dwordx2 v[34:35], v[2:3], off offset:64
	v_mul_f32_e32 v2, v6, v36
	v_mul_f32_e32 v3, v7, v36
	v_cvt_pk_bf16_f32 v2, v2, v3
	v_mul_f32_e32 v3, v8, v36
	v_mul_f32_e32 v4, v9, v36
	v_cvt_pk_bf16_f32 v3, v3, v4
	global_store_dwordx2 v[34:35], v[2:3], off offset:80
	v_mul_f32_e32 v2, v10, v36
	v_mul_f32_e32 v3, v11, v36
	v_cvt_pk_bf16_f32 v2, v2, v3
	v_mul_f32_e32 v3, v12, v36
	v_mul_f32_e32 v4, v13, v36
	v_cvt_pk_bf16_f32 v3, v3, v4
	global_store_dwordx2 v[34:35], v[2:3], off offset:96
	v_mul_f32_e32 v2, v14, v36
	v_mul_f32_e32 v3, v15, v36
	v_cvt_pk_bf16_f32 v2, v2, v3
	v_mul_f32_e32 v3, v16, v36
	v_mul_f32_e32 v4, v17, v36
	v_cvt_pk_bf16_f32 v3, v3, v4
	global_store_dwordx2 v[34:35], v[2:3], off offset:112
	s_cbranch_scc0 .LBB0_821
.LBB0_813:
	s_ashr_i32 s50, s2, 7
	s_and_b32 s49, s2, 3
	s_bfe_u32 s80, s2, 0x50002
	s_ashr_i32 s51, s50, 31
	s_lshl_b32 s48, s49, 2
	s_lshl_b64 s[88:89], s[50:51], 12
	v_lshl_or_b32 v150, s80, 7, v128
	s_add_i32 s48, s48, s83
	v_or_b32_e32 v8, s88, v150
	v_mov_b32_e32 v3, s89
	s_lshl_b32 s50, s48, 6
	v_or_b32_e32 v2, s97, v8
	s_ashr_i32 s51, s50, 31
	v_lshlrev_b64 v[6:7], 11, v[2:3]
	v_or_b32_e32 v2, s87, v8
	v_lshl_add_u64 v[4:5], s[50:51], 1, v[110:111]
	v_lshlrev_b64 v[2:3], 11, v[2:3]
	v_lshl_add_u64 v[6:7], v[4:5], 0, v[6:7]
	v_lshl_add_u64 v[2:3], v[4:5], 0, v[2:3]
	global_load_dwordx4 v[34:37], v[6:7], off
	global_load_dwordx4 v[106:109], v[6:7], off offset:32
	global_load_dwordx4 v[102:105], v[6:7], off offset:64
	global_load_dwordx4 v[98:101], v[6:7], off offset:96
	global_load_dwordx4 v[94:97], v[2:3], off
	global_load_dwordx4 v[90:93], v[2:3], off offset:32
	global_load_dwordx4 v[86:89], v[2:3], off offset:64
	global_load_dwordx4 v[82:85], v[2:3], off offset:96
	v_add_co_u32_e64 v2, vcc, s80, -1
	v_ashrrev_i32_e32 v3, 31, v2
	v_lshlrev_b64 v[2:3], 7, v[2:3]
	s_lshl_b32 s94, s49, 7
	v_lshl_add_u64 v[16:17], v[2:3], 0, s[88:89]
	v_lshl_add_u64 v[18:19], v[114:115], 0, s[94:95]
	v_lshl_add_u64 v[20:21], v[116:117], 0, s[94:95]
	v_mov_b32_e32 v38, 0
	v_mov_b32_e32 v39, 0
	v_mov_b32_e32 v40, 0
	v_mov_b32_e32 v41, 0
	v_mov_b32_e32 v42, 0
	v_mov_b32_e32 v43, 0
	v_mov_b32_e32 v44, 0
	v_mov_b32_e32 v45, 0
	v_mov_b32_e32 v46, 0
	v_mov_b32_e32 v47, 0
	v_mov_b32_e32 v48, 0
	v_mov_b32_e32 v49, 0
	v_mov_b32_e32 v50, 0
	v_mov_b32_e32 v51, 0
	v_mov_b32_e32 v52, 0
	v_mov_b32_e32 v53, 0
	v_mov_b32_e32 v54, 0
	v_mov_b32_e32 v55, 0
	v_mov_b32_e32 v56, 0
	v_mov_b32_e32 v57, 0
	v_mov_b32_e32 v58, 0
	v_mov_b32_e32 v59, 0
	v_mov_b32_e32 v60, 0
	v_mov_b32_e32 v61, 0
	v_mov_b32_e32 v62, 0
	v_mov_b32_e32 v63, 0
	v_mov_b32_e32 v64, 0
	v_mov_b32_e32 v65, 0
	v_mov_b32_e32 v66, 0
	v_mov_b32_e32 v67, 0
	v_mov_b32_e32 v68, 0
	v_mov_b32_e32 v69, 0
	s_or_b64 s[54:55], s[4:5], vcc
	s_and_saveexec_b64 s[52:53], s[54:55]
	v_lshl_add_u64 v[70:71], v[16:17], 0, v[112:113]
	v_lshlrev_b64 v[70:71], 9, v[70:71]
	v_lshl_add_u64 v[72:73], v[20:21], 0, v[70:71]
	v_lshl_add_u64 v[70:71], v[18:19], 0, v[70:71]
	global_load_dwordx4 v[38:41], v[70:71], off
	global_load_dwordx4 v[54:57], v[72:73], off
	s_or_b64 exec, exec, s[52:53]
	s_or_b64 s[54:55], s[6:7], vcc
	s_and_saveexec_b64 s[52:53], s[54:55]
	v_lshl_add_u64 v[70:71], v[16:17], 0, v[120:121]
	v_lshlrev_b64 v[70:71], 9, v[70:71]
	v_lshl_add_u64 v[72:73], v[20:21], 0, v[70:71]
	v_lshl_add_u64 v[70:71], v[18:19], 0, v[70:71]
	global_load_dwordx4 v[42:45], v[70:71], off
	global_load_dwordx4 v[58:61], v[72:73], off
	s_or_b64 exec, exec, s[52:53]
	s_or_b64 s[54:55], s[8:9], vcc
	s_and_saveexec_b64 s[52:53], s[54:55]
	v_lshl_add_u64 v[70:71], v[16:17], 0, v[122:123]
	v_lshlrev_b64 v[70:71], 9, v[70:71]
	v_lshl_add_u64 v[72:73], v[20:21], 0, v[70:71]
	v_lshl_add_u64 v[70:71], v[18:19], 0, v[70:71]
	global_load_dwordx4 v[46:49], v[70:71], off
	global_load_dwordx4 v[62:65], v[72:73], off
	s_or_b64 exec, exec, s[52:53]
	s_or_b64 s[54:55], s[10:11], vcc
	s_and_saveexec_b64 s[52:53], s[54:55]
	v_lshl_add_u64 v[70:71], v[16:17], 0, v[124:125]
	v_lshlrev_b64 v[70:71], 9, v[70:71]
	v_lshl_add_u64 v[72:73], v[20:21], 0, v[70:71]
	v_lshl_add_u64 v[70:71], v[18:19], 0, v[70:71]
	global_load_dwordx4 v[50:53], v[70:71], off
	global_load_dwordx4 v[66:69], v[72:73], off
	s_or_b64 exec, exec, s[52:53]
	s_barrier
	s_waitcnt vmcnt(7)
	ds_write_b128 v148, v[38:41]
	s_waitcnt vmcnt(6)
	ds_write_b16 v138, v54 offset:36864
	ds_write_b16_d16_hi v138, v54 offset:37392
	ds_write_b16 v138, v55 offset:37920
	ds_write_b16_d16_hi v138, v55 offset:38448
	ds_write_b16 v138, v56 offset:38976
	ds_write_b16_d16_hi v138, v56 offset:39504
	ds_write_b16 v138, v57 offset:40032
	ds_write_b16_d16_hi v138, v57 offset:40560
	s_waitcnt vmcnt(5)
	ds_write_b128 v148, v[42:45] offset:9216
	s_waitcnt vmcnt(4)
	ds_write_b16 v139, v58 offset:36864
	ds_write_b16_d16_hi v139, v58 offset:37392
	ds_write_b16 v139, v59 offset:37920
	ds_write_b16_d16_hi v139, v59 offset:38448
	ds_write_b16 v139, v60 offset:38976
	ds_write_b16_d16_hi v139, v60 offset:39504
	ds_write_b16 v139, v61 offset:40032
	ds_write_b16_d16_hi v139, v61 offset:40560
	s_waitcnt vmcnt(3)
	ds_write_b128 v148, v[46:49] offset:18432
	s_waitcnt vmcnt(2)
	ds_write_b16 v140, v62 offset:36864
	ds_write_b16_d16_hi v140, v62 offset:37392
	ds_write_b16 v140, v63 offset:37920
	ds_write_b16_d16_hi v140, v63 offset:38448
	ds_write_b16 v140, v64 offset:38976
	ds_write_b16_d16_hi v140, v64 offset:39504
	ds_write_b16 v140, v65 offset:40032
	ds_write_b16_d16_hi v140, v65 offset:40560
	s_waitcnt vmcnt(1)
	ds_write_b128 v148, v[50:53] offset:27648
	s_waitcnt vmcnt(0)
	ds_write_b16 v141, v66 offset:36864
	ds_write_b16_d16_hi v141, v66 offset:37392
	ds_write_b16 v141, v67 offset:37920
	ds_write_b16_d16_hi v141, v67 offset:38448
	ds_write_b16 v141, v68 offset:38976
	ds_write_b16_d16_hi v141, v68 offset:39504
	ds_write_b16 v141, v69 offset:40032
	ds_write_b16_d16_hi v141, v69 offset:40560
	s_branch .LBB0_812
